# GEMM units: accumulators zeroed with 64-bit moves (63 fewer VALU per unit), plus redundant lgkmcnt(0) at MFMA segment heads removed
# speedup vs baseline: 1.0071x; 1.0071x over previous
;     __host__ __device__ bool next(int i, Unit& u) const { if (i >= nu) return false; u.pm = 16 * x + (s >> 1); u.pn = pn0 + nu * (s & 1) + i; return true; }
;     __host__ __device__ bool next(int i, Unit& u) const { if (!StaticOrder::next(i, u)) return false; u.pn += pn0; return true; }
; template <class Epi, class Sched, bool ALIGN_EPI = false, bool SP2 = false>
; __device__ __forceinline__ void gemm_phase(PG8_LAS unsigned char* lds, const Gemm g, const Sched& S, const Epi& E, int tid_in) {
;     ...
;         const bool has_next = S.next(ui + 1, nxt);
;         const char* nA = has_next ? (const char*)g.A + (size_t)nxt.pm * tstep : cA; const char* nB = has_next ? (const char*)g.Bt + (size_t)nxt.pn * tstep : cB;
;     ...
;         for (int a = 0; a < 2; ++a)
; #pragma unroll
;             for (int b = 0; b < 2; ++b)
; #pragma unroll
;                 for (int m = 0; m < 4; ++m)
; #pragma unroll
;                     for (int n = 0; n < 2; ++n) acc[a][b][m][n] = (f32x4){0.f, 0.f, 0.f, 0.f};
;         cur = nxt; cA = nA; cB = nB; ++ui;
.LBB0_134:
	s_ashr_i32 s43, s42, 31
	s_lshl_b64 s[44:45], s[42:43], 20
	s_add_u32 s44, s52, s44
	s_addc_u32 s45, s69, s45
	s_and_b64 s[46:47], s[0:1], exec
	s_cselect_b32 s17, s45, s65
	s_cselect_b32 s43, s44, s64
	s_ashr_i32 s41, s40, 31
	s_lshl_b64 s[46:47], s[40:41], 20
	s_add_u32 s46, s26, s46
	s_addc_u32 s47, s27, s47
	s_and_b64 s[62:63], s[0:1], exec
	s_cselect_b32 s41, s47, s93
	s_cselect_b32 s72, s46, s92
	s_add_u32 s64, s64, 0x80080
	s_addc_u32 s65, s65, 0
	s_add_u32 s73, s92, 0x100
	v_mov_b32_e32 v0, 0
	s_addc_u32 s74, s93, 0
	s_mov_b32 s75, -2
	v_mov_b32_e32 v1, 0
	v_mov_b64_e32 v[2:3], 0
	v_mov_b64_e32 v[4:5], 0
	v_mov_b64_e32 v[6:7], 0
	v_mov_b64_e32 v[8:9], 0
	v_mov_b64_e32 v[10:11], 0
	v_mov_b64_e32 v[12:13], 0
	v_mov_b64_e32 v[14:15], 0
	v_mov_b64_e32 v[16:17], 0
	v_mov_b64_e32 v[18:19], 0
	v_mov_b64_e32 v[20:21], 0
	v_mov_b64_e32 v[22:23], 0
	v_mov_b64_e32 v[24:25], 0
	v_mov_b64_e32 v[26:27], 0
	v_mov_b64_e32 v[28:29], 0
	v_mov_b64_e32 v[30:31], 0
	v_mov_b64_e32 v[32:33], 0
	v_mov_b64_e32 v[34:35], 0
	v_mov_b64_e32 v[36:37], 0
	v_mov_b64_e32 v[38:39], 0
	v_mov_b64_e32 v[40:41], 0
	v_mov_b64_e32 v[42:43], 0
	v_mov_b64_e32 v[44:45], 0
	v_mov_b64_e32 v[46:47], 0
	v_mov_b64_e32 v[48:49], 0
	v_mov_b64_e32 v[50:51], 0
	v_mov_b64_e32 v[52:53], 0
	v_mov_b64_e32 v[54:55], 0
	v_mov_b64_e32 v[56:57], 0
	v_mov_b64_e32 v[58:59], 0
	v_mov_b64_e32 v[60:61], 0
	v_mov_b64_e32 v[62:63], 0
	v_mov_b64_e32 v[64:65], 0
	v_mov_b64_e32 v[66:67], 0
	v_mov_b64_e32 v[68:69], 0
	v_mov_b64_e32 v[70:71], 0
	v_mov_b64_e32 v[72:73], 0
	v_mov_b64_e32 v[74:75], 0
	v_mov_b64_e32 v[76:77], 0
	v_mov_b64_e32 v[78:79], 0
	v_mov_b64_e32 v[80:81], 0
	v_mov_b64_e32 v[82:83], 0
	v_mov_b64_e32 v[84:85], 0
	v_mov_b64_e32 v[86:87], 0
	v_mov_b64_e32 v[88:89], 0
	v_mov_b64_e32 v[90:91], 0
	v_mov_b64_e32 v[92:93], 0
	v_mov_b64_e32 v[94:95], 0
	v_mov_b64_e32 v[98:99], 0
	v_mov_b64_e32 v[100:101], 0
	v_mov_b64_e32 v[102:103], 0
	v_mov_b64_e32 v[104:105], 0
	v_mov_b64_e32 v[106:107], 0
	v_mov_b64_e32 v[108:109], 0
	v_mov_b64_e32 v[110:111], 0
	v_mov_b64_e32 v[112:113], 0
	v_mov_b64_e32 v[114:115], 0
	v_mov_b64_e32 v[116:117], 0
	v_mov_b64_e32 v[118:119], 0
	v_mov_b64_e32 v[120:121], 0
	v_mov_b64_e32 v[122:123], 0
	v_mov_b64_e32 v[124:125], 0
	v_mov_b64_e32 v[126:127], 0
	v_mov_b64_e32 v[128:129], 0

;     __host__ __device__ bool next(int i, Unit& u) const { if (i >= nu) return false; u.pm = 16 * x + (s >> 1); u.pn = pn0 + nu * (s & 1) + i; return true; }
;     __host__ __device__ bool next(int i, Unit& u) const { if (!StaticOrder::next(i, u)) return false; u.pn += pn0; return true; }
; template <class Epi, class Sched, bool ALIGN_EPI = false, bool SP2 = false>
; __device__ __forceinline__ void gemm_phase(PG8_LAS unsigned char* lds, const Gemm g, const Sched& S, const Epi& E, int tid_in) {
;     ...
;         const bool has_next = S.next(ui + 1, nxt);
;         const char* nA = has_next ? (const char*)g.A + (size_t)nxt.pm * tstep : cA; const char* nB = has_next ? (const char*)g.Bt + (size_t)nxt.pn * tstep : cB;
;     ...
;         for (int a = 0; a < 2; ++a)
; #pragma unroll
;             for (int b = 0; b < 2; ++b)
; #pragma unroll
;                 for (int m = 0; m < 4; ++m)
; #pragma unroll
;                     for (int n = 0; n < 2; ++n) acc[a][b][m][n] = (f32x4){0.f, 0.f, 0.f, 0.f};
;         cur = nxt; cA = nA; cB = nB; ++ui;
.LBB0_566:
	s_ashr_i32 s19, s18, 31
	s_lshl_b64 s[20:21], s[18:19], 20
	s_add_u32 s20, s35, s20
	s_addc_u32 s21, s38, s21
	s_and_b64 s[22:23], s[0:1], exec
	s_cselect_b32 s19, s21, s27
	s_cselect_b32 s47, s20, s26
	s_ashr_i32 s17, s16, 31
	s_lshl_b64 s[22:23], s[16:17], 20
	s_add_u32 s22, s10, s22
	s_addc_u32 s23, s11, s23
	s_and_b64 s[30:31], s[0:1], exec
	s_cselect_b32 s17, s23, s29
	s_cselect_b32 s52, s22, s28
	s_add_u32 s26, s26, 0x80080
	s_addc_u32 s27, s27, 0
	s_add_u32 s64, s28, 0x100
	v_mov_b32_e32 v0, 0
	s_addc_u32 s65, s29, 0
	s_mov_b32 s66, -2
	v_mov_b32_e32 v1, 0
	v_mov_b64_e32 v[2:3], 0
	v_mov_b64_e32 v[4:5], 0
	v_mov_b64_e32 v[6:7], 0
	v_mov_b64_e32 v[8:9], 0
	v_mov_b64_e32 v[10:11], 0
	v_mov_b64_e32 v[12:13], 0
	v_mov_b64_e32 v[14:15], 0
	v_mov_b64_e32 v[16:17], 0
	v_mov_b64_e32 v[18:19], 0
	v_mov_b64_e32 v[20:21], 0
	v_mov_b64_e32 v[22:23], 0
	v_mov_b64_e32 v[24:25], 0
	v_mov_b64_e32 v[26:27], 0
	v_mov_b64_e32 v[28:29], 0
	v_mov_b64_e32 v[30:31], 0
	v_mov_b64_e32 v[32:33], 0
	v_mov_b64_e32 v[34:35], 0
	v_mov_b64_e32 v[36:37], 0
	v_mov_b64_e32 v[38:39], 0
	v_mov_b64_e32 v[40:41], 0
	v_mov_b64_e32 v[42:43], 0
	v_mov_b64_e32 v[44:45], 0
	v_mov_b64_e32 v[46:47], 0
	v_mov_b64_e32 v[48:49], 0
	v_mov_b64_e32 v[50:51], 0
	v_mov_b64_e32 v[52:53], 0
	v_mov_b64_e32 v[54:55], 0
	v_mov_b64_e32 v[56:57], 0
	v_mov_b64_e32 v[58:59], 0
	v_mov_b64_e32 v[60:61], 0
	v_mov_b64_e32 v[62:63], 0
	v_mov_b64_e32 v[64:65], 0
	v_mov_b64_e32 v[66:67], 0
	v_mov_b64_e32 v[68:69], 0
	v_mov_b64_e32 v[70:71], 0
	v_mov_b64_e32 v[72:73], 0
	v_mov_b64_e32 v[74:75], 0
	v_mov_b64_e32 v[76:77], 0
	v_mov_b64_e32 v[78:79], 0
	v_mov_b64_e32 v[80:81], 0
	v_mov_b64_e32 v[82:83], 0
	v_mov_b64_e32 v[84:85], 0
	v_mov_b64_e32 v[86:87], 0
	v_mov_b64_e32 v[88:89], 0
	v_mov_b64_e32 v[90:91], 0
	v_mov_b64_e32 v[92:93], 0
	v_mov_b64_e32 v[94:95], 0
	v_mov_b64_e32 v[98:99], 0
	v_mov_b64_e32 v[100:101], 0
	v_mov_b64_e32 v[102:103], 0
	v_mov_b64_e32 v[104:105], 0
	v_mov_b64_e32 v[106:107], 0
	v_mov_b64_e32 v[108:109], 0
	v_mov_b64_e32 v[110:111], 0
	v_mov_b64_e32 v[112:113], 0
	v_mov_b64_e32 v[114:115], 0
	v_mov_b64_e32 v[116:117], 0
	v_mov_b64_e32 v[118:119], 0
	v_mov_b64_e32 v[120:121], 0
	v_mov_b64_e32 v[122:123], 0
	v_mov_b64_e32 v[124:125], 0
	v_mov_b64_e32 v[126:127], 0
	v_mov_b64_e32 v[128:129], 0

;     __host__ __device__ bool next(int i, Unit& u) const { if (i >= nu) return false; u.pm = 16 * x + (s >> 1); u.pn = pn0 + nu * (s & 1) + i; return true; }
;     __host__ __device__ bool next(int i, Unit& u) const { if (!StaticOrder::next(i, u)) return false; u.pn += pn0; return true; }
; template <class Epi, class Sched, bool ALIGN_EPI = false, bool SP2 = false>
; __device__ __forceinline__ void gemm_phase(PG8_LAS unsigned char* lds, const Gemm g, const Sched& S, const Epi& E, int tid_in) {
;     ...
;         const bool has_next = S.next(ui + 1, nxt);
;         const char* nA = has_next ? (const char*)g.A + (size_t)nxt.pm * tstep : cA; const char* nB = has_next ? (const char*)g.Bt + (size_t)nxt.pn * tstep : cB;
;     ...
;         for (int a = 0; a < 2; ++a)
; #pragma unroll
;             for (int b = 0; b < 2; ++b)
; #pragma unroll
;                 for (int m = 0; m < 4; ++m)
; #pragma unroll
;                     for (int n = 0; n < 2; ++n) acc[a][b][m][n] = (f32x4){0.f, 0.f, 0.f, 0.f};
;         cur = nxt; cA = nA; cB = nB; ++ui;
.LBB0_631:
	s_ashr_i32 s21, s20, 31
	s_lshl_b64 s[22:23], s[20:21], 20
	s_add_u32 s22, s42, s22
	s_addc_u32 s23, s43, s23
	s_and_b64 s[24:25], s[0:1], exec
	s_cselect_b32 s21, s23, s29
	s_cselect_b32 s67, s22, s28
	s_ashr_i32 s19, s18, 31
	s_lshl_b64 s[24:25], s[18:19], 20
	s_add_u32 s24, s14, s24
	s_addc_u32 s25, s15, s25
	s_and_b64 s[34:35], s[0:1], exec
	s_cselect_b32 s19, s25, s31
	s_cselect_b32 s69, s24, s30
	s_add_u32 s28, s28, 0x80080
	s_addc_u32 s29, s29, 0
	s_add_u32 s70, s30, 0x100
	v_mov_b32_e32 v0, 0
	s_addc_u32 s71, s31, 0
	s_mov_b32 s72, -2
	v_mov_b32_e32 v1, 0
	v_mov_b64_e32 v[2:3], 0
	v_mov_b64_e32 v[4:5], 0
	v_mov_b64_e32 v[6:7], 0
	v_mov_b64_e32 v[8:9], 0
	v_mov_b64_e32 v[10:11], 0
	v_mov_b64_e32 v[12:13], 0
	v_mov_b64_e32 v[14:15], 0
	v_mov_b64_e32 v[16:17], 0
	v_mov_b64_e32 v[18:19], 0
	v_mov_b64_e32 v[20:21], 0
	v_mov_b64_e32 v[22:23], 0
	v_mov_b64_e32 v[24:25], 0
	v_mov_b64_e32 v[26:27], 0
	v_mov_b64_e32 v[28:29], 0
	v_mov_b64_e32 v[30:31], 0
	v_mov_b64_e32 v[32:33], 0
	v_mov_b64_e32 v[34:35], 0
	v_mov_b64_e32 v[36:37], 0
	v_mov_b64_e32 v[38:39], 0
	v_mov_b64_e32 v[40:41], 0
	v_mov_b64_e32 v[42:43], 0
	v_mov_b64_e32 v[44:45], 0
	v_mov_b64_e32 v[46:47], 0
	v_mov_b64_e32 v[48:49], 0
	v_mov_b64_e32 v[50:51], 0
	v_mov_b64_e32 v[52:53], 0
	v_mov_b64_e32 v[54:55], 0
	v_mov_b64_e32 v[56:57], 0
	v_mov_b64_e32 v[58:59], 0
	v_mov_b64_e32 v[60:61], 0
	v_mov_b64_e32 v[62:63], 0
	v_mov_b64_e32 v[64:65], 0
	v_mov_b64_e32 v[66:67], 0
	v_mov_b64_e32 v[68:69], 0
	v_mov_b64_e32 v[70:71], 0
	v_mov_b64_e32 v[72:73], 0
	v_mov_b64_e32 v[74:75], 0
	v_mov_b64_e32 v[76:77], 0
	v_mov_b64_e32 v[78:79], 0
	v_mov_b64_e32 v[80:81], 0
	v_mov_b64_e32 v[82:83], 0
	v_mov_b64_e32 v[84:85], 0
	v_mov_b64_e32 v[86:87], 0
	v_mov_b64_e32 v[88:89], 0
	v_mov_b64_e32 v[90:91], 0
	v_mov_b64_e32 v[92:93], 0
	v_mov_b64_e32 v[94:95], 0
	v_mov_b64_e32 v[98:99], 0
	v_mov_b64_e32 v[100:101], 0
	v_mov_b64_e32 v[102:103], 0
	v_mov_b64_e32 v[104:105], 0
	v_mov_b64_e32 v[106:107], 0
	v_mov_b64_e32 v[108:109], 0
	v_mov_b64_e32 v[110:111], 0
	v_mov_b64_e32 v[112:113], 0
	v_mov_b64_e32 v[114:115], 0
	v_mov_b64_e32 v[116:117], 0
	v_mov_b64_e32 v[118:119], 0
	v_mov_b64_e32 v[120:121], 0
	v_mov_b64_e32 v[122:123], 0
	v_mov_b64_e32 v[124:125], 0
	v_mov_b64_e32 v[126:127], 0
	v_mov_b64_e32 v[128:129], 0

;     __host__ __device__ bool next(int i, Unit& u) const { if (i >= nu) return false; u.pm = 16 * x + (s >> 1); u.pn = pn0 + nu * (s & 1) + i; return true; }
;     __host__ __device__ bool next(int i, Unit& u) const { if (!StaticOrder::next(i, u)) return false; u.pn += pn0; return true; }
; template <class Epi, class Sched, bool ALIGN_EPI = false, bool SP2 = false>
; __device__ __forceinline__ void gemm_phase(PG8_LAS unsigned char* lds, const Gemm g, const Sched& S, const Epi& E, int tid_in) {
;     ...
;         const bool has_next = S.next(ui + 1, nxt);
;         const char* nA = has_next ? (const char*)g.A + (size_t)nxt.pm * tstep : cA; const char* nB = has_next ? (const char*)g.Bt + (size_t)nxt.pn * tstep : cB;
;     ...
;         for (int a = 0; a < 2; ++a)
; #pragma unroll
;             for (int b = 0; b < 2; ++b)
; #pragma unroll
;                 for (int m = 0; m < 4; ++m)
; #pragma unroll
;                     for (int n = 0; n < 2; ++n) acc[a][b][m][n] = (f32x4){0.f, 0.f, 0.f, 0.f};
;         cur = nxt; cA = nA; cB = nB; ++ui;
.LBB0_748:
	s_ashr_i32 s17, s16, 31
	s_lshl_b64 s[18:19], s[16:17], 20
	s_add_u32 s18, s31, s18
	s_addc_u32 s19, s34, s19
	s_and_b64 s[20:21], s[0:1], exec
	s_cselect_b32 s17, s19, s23
	s_cselect_b32 s43, s18, s22
	s_ashr_i32 s15, s14, 31
	s_lshl_b64 s[20:21], s[14:15], 20
	s_add_u32 s20, s2, s20
	s_addc_u32 s21, s3, s21
	s_and_b64 s[26:27], s[0:1], exec
	s_cselect_b32 s15, s21, s25
	s_cselect_b32 s44, s20, s24
	s_add_u32 s22, s22, 0x80080
	s_addc_u32 s23, s23, 0
	s_add_u32 s45, s24, 0x100
	v_mov_b32_e32 v0, 0
	s_addc_u32 s46, s25, 0
	s_mov_b32 s47, -2
	v_mov_b32_e32 v1, 0
	v_mov_b64_e32 v[2:3], 0
	v_mov_b64_e32 v[4:5], 0
	v_mov_b64_e32 v[6:7], 0
	v_mov_b64_e32 v[8:9], 0
	v_mov_b64_e32 v[10:11], 0
	v_mov_b64_e32 v[12:13], 0
	v_mov_b64_e32 v[14:15], 0
	v_mov_b64_e32 v[16:17], 0
	v_mov_b64_e32 v[18:19], 0
	v_mov_b64_e32 v[20:21], 0
	v_mov_b64_e32 v[22:23], 0
	v_mov_b64_e32 v[24:25], 0
	v_mov_b64_e32 v[26:27], 0
	v_mov_b64_e32 v[28:29], 0
	v_mov_b64_e32 v[30:31], 0
	v_mov_b64_e32 v[32:33], 0
	v_mov_b64_e32 v[34:35], 0
	v_mov_b64_e32 v[36:37], 0
	v_mov_b64_e32 v[38:39], 0
	v_mov_b64_e32 v[40:41], 0
	v_mov_b64_e32 v[42:43], 0
	v_mov_b64_e32 v[44:45], 0
	v_mov_b64_e32 v[46:47], 0
	v_mov_b64_e32 v[48:49], 0
	v_mov_b64_e32 v[50:51], 0
	v_mov_b64_e32 v[52:53], 0
	v_mov_b64_e32 v[54:55], 0
	v_mov_b64_e32 v[56:57], 0
	v_mov_b64_e32 v[58:59], 0
	v_mov_b64_e32 v[60:61], 0
	v_mov_b64_e32 v[62:63], 0
	v_mov_b64_e32 v[64:65], 0
	v_mov_b64_e32 v[66:67], 0
	v_mov_b64_e32 v[68:69], 0
	v_mov_b64_e32 v[70:71], 0
	v_mov_b64_e32 v[72:73], 0
	v_mov_b64_e32 v[74:75], 0
	v_mov_b64_e32 v[76:77], 0
	v_mov_b64_e32 v[78:79], 0
	v_mov_b64_e32 v[80:81], 0
	v_mov_b64_e32 v[82:83], 0
	v_mov_b64_e32 v[84:85], 0
	v_mov_b64_e32 v[86:87], 0
	v_mov_b64_e32 v[88:89], 0
	v_mov_b64_e32 v[90:91], 0
	v_mov_b64_e32 v[92:93], 0
	v_mov_b64_e32 v[94:95], 0
	v_mov_b64_e32 v[98:99], 0
	v_mov_b64_e32 v[100:101], 0
	v_mov_b64_e32 v[102:103], 0
	v_mov_b64_e32 v[104:105], 0
	v_mov_b64_e32 v[106:107], 0
	v_mov_b64_e32 v[108:109], 0
	v_mov_b64_e32 v[110:111], 0
	v_mov_b64_e32 v[112:113], 0
	v_mov_b64_e32 v[114:115], 0
	v_mov_b64_e32 v[116:117], 0
	v_mov_b64_e32 v[118:119], 0
	v_mov_b64_e32 v[120:121], 0
	v_mov_b64_e32 v[122:123], 0
	v_mov_b64_e32 v[124:125], 0
	v_mov_b64_e32 v[126:127], 0
	v_mov_b64_e32 v[128:129], 0

;     __host__ __device__ bool next(int i, Unit& u) const { if (i >= nu) return false; u.pm = 16 * x + (s >> 1); u.pn = pn0 + nu * (s & 1) + i; return true; }
;     __host__ __device__ bool next(int i, Unit& u) const { if (!StaticOrder::next(i, u)) return false; u.pn += pn0; return true; }
; template <class Epi, class Sched, bool ALIGN_EPI = false, bool SP2 = false>
; __device__ __forceinline__ void gemm_phase(PG8_LAS unsigned char* lds, const Gemm g, const Sched& S, const Epi& E, int tid_in) {
;     ...
;         const bool has_next = S.next(ui + 1, nxt);
;         const char* nA = has_next ? (const char*)g.A + (size_t)nxt.pm * tstep : cA; const char* nB = has_next ? (const char*)g.Bt + (size_t)nxt.pn * tstep : cB;
;     ...
;         for (int a = 0; a < 2; ++a)
; #pragma unroll
;             for (int b = 0; b < 2; ++b)
; #pragma unroll
;                 for (int m = 0; m < 4; ++m)
; #pragma unroll
;                     for (int n = 0; n < 2; ++n) acc[a][b][m][n] = (f32x4){0.f, 0.f, 0.f, 0.f};
;         cur = nxt; cA = nA; cB = nB; ++ui;
.LBB0_978:
	s_ashr_i32 s17, s16, 31
	s_lshl_b64 s[18:19], s[16:17], 20
	s_add_u32 s18, s34, s18
	s_addc_u32 s19, s35, s19
	s_and_b64 s[20:21], s[0:1], exec
	s_cselect_b32 s17, s19, s25
	s_cselect_b32 s45, s18, s24
	s_ashr_i32 s15, s14, 31
	s_lshl_b64 s[20:21], s[14:15], 20
	s_add_u32 s20, s6, s20
	s_addc_u32 s21, s7, s21
	s_and_b64 s[28:29], s[0:1], exec
	s_cselect_b32 s15, s21, s27
	s_cselect_b32 s46, s20, s26
	s_add_u32 s24, s24, 0x80080
	s_addc_u32 s25, s25, 0
	s_add_u32 s47, s26, 0x100
	v_mov_b32_e32 v0, 0
	s_addc_u32 s52, s27, 0
	s_mov_b32 s64, -2
	v_mov_b32_e32 v1, 0
	v_mov_b64_e32 v[2:3], 0
	v_mov_b64_e32 v[4:5], 0
	v_mov_b64_e32 v[6:7], 0
	v_mov_b64_e32 v[8:9], 0
	v_mov_b64_e32 v[10:11], 0
	v_mov_b64_e32 v[12:13], 0
	v_mov_b64_e32 v[14:15], 0
	v_mov_b64_e32 v[16:17], 0
	v_mov_b64_e32 v[18:19], 0
	v_mov_b64_e32 v[20:21], 0
	v_mov_b64_e32 v[22:23], 0
	v_mov_b64_e32 v[24:25], 0
	v_mov_b64_e32 v[26:27], 0
	v_mov_b64_e32 v[28:29], 0
	v_mov_b64_e32 v[30:31], 0
	v_mov_b64_e32 v[32:33], 0
	v_mov_b64_e32 v[34:35], 0
	v_mov_b64_e32 v[36:37], 0
	v_mov_b64_e32 v[38:39], 0
	v_mov_b64_e32 v[40:41], 0
	v_mov_b64_e32 v[42:43], 0
	v_mov_b64_e32 v[44:45], 0
	v_mov_b64_e32 v[46:47], 0
	v_mov_b64_e32 v[48:49], 0
	v_mov_b64_e32 v[50:51], 0
	v_mov_b64_e32 v[52:53], 0
	v_mov_b64_e32 v[54:55], 0
	v_mov_b64_e32 v[56:57], 0
	v_mov_b64_e32 v[58:59], 0
	v_mov_b64_e32 v[60:61], 0
	v_mov_b64_e32 v[62:63], 0
	v_mov_b64_e32 v[64:65], 0
	v_mov_b64_e32 v[66:67], 0
	v_mov_b64_e32 v[68:69], 0
	v_mov_b64_e32 v[70:71], 0
	v_mov_b64_e32 v[72:73], 0
	v_mov_b64_e32 v[74:75], 0
	v_mov_b64_e32 v[76:77], 0
	v_mov_b64_e32 v[78:79], 0
	v_mov_b64_e32 v[80:81], 0
	v_mov_b64_e32 v[82:83], 0
	v_mov_b64_e32 v[84:85], 0
	v_mov_b64_e32 v[86:87], 0
	v_mov_b64_e32 v[88:89], 0
	v_mov_b64_e32 v[90:91], 0
	v_mov_b64_e32 v[92:93], 0
	v_mov_b64_e32 v[94:95], 0
	v_mov_b64_e32 v[98:99], 0
	v_mov_b64_e32 v[100:101], 0
	v_mov_b64_e32 v[102:103], 0
	v_mov_b64_e32 v[104:105], 0
	v_mov_b64_e32 v[106:107], 0
	v_mov_b64_e32 v[108:109], 0
	v_mov_b64_e32 v[110:111], 0
	v_mov_b64_e32 v[112:113], 0
	v_mov_b64_e32 v[114:115], 0
	v_mov_b64_e32 v[116:117], 0
	v_mov_b64_e32 v[118:119], 0
	v_mov_b64_e32 v[120:121], 0
	v_mov_b64_e32 v[122:123], 0
	v_mov_b64_e32 v[124:125], 0
	v_mov_b64_e32 v[126:127], 0
	v_mov_b64_e32 v[128:129], 0

; template <class Epi, class Sched, bool ALIGN_EPI = false, bool SP2 = false>
; __device__ __forceinline__ void gemm_phase(PG8_LAS unsigned char* lds, const Gemm g, const Sched& S, const Epi& E, int tid_in) {
;     ...
;         for (int a = 0; a < 2; ++a)
; #pragma unroll
;             for (int b = 0; b < 2; ++b)
; #pragma unroll
;                 for (int m = 0; m < 4; ++m)
; #pragma unroll
;                     for (int n = 0; n < 2; ++n) acc[a][b][m][n] = (f32x4){0.f, 0.f, 0.f, 0.f};
;         cur = nxt; cA = nA; cB = nB; ++ui;
.LBB0_1099:
	s_add_u32 s45, s20, 0x100
	v_mov_b32_e32 v0, 0
	s_addc_u32 s46, s21, 0
	s_mov_b32 s47, -2
	v_mov_b32_e32 v1, 0
	v_mov_b64_e32 v[2:3], 0
	v_mov_b64_e32 v[4:5], 0
	v_mov_b64_e32 v[6:7], 0
	v_mov_b64_e32 v[8:9], 0
	v_mov_b64_e32 v[10:11], 0
	v_mov_b64_e32 v[12:13], 0
	v_mov_b64_e32 v[14:15], 0
	v_mov_b64_e32 v[16:17], 0
	v_mov_b64_e32 v[18:19], 0
	v_mov_b64_e32 v[20:21], 0
	v_mov_b64_e32 v[22:23], 0
	v_mov_b64_e32 v[24:25], 0
	v_mov_b64_e32 v[26:27], 0
	v_mov_b64_e32 v[28:29], 0
	v_mov_b64_e32 v[30:31], 0
	v_mov_b64_e32 v[32:33], 0
	v_mov_b64_e32 v[34:35], 0
	v_mov_b64_e32 v[36:37], 0
	v_mov_b64_e32 v[38:39], 0
	v_mov_b64_e32 v[40:41], 0
	v_mov_b64_e32 v[42:43], 0
	v_mov_b64_e32 v[44:45], 0
	v_mov_b64_e32 v[46:47], 0
	v_mov_b64_e32 v[48:49], 0
	v_mov_b64_e32 v[50:51], 0
	v_mov_b64_e32 v[52:53], 0
	v_mov_b64_e32 v[54:55], 0
	v_mov_b64_e32 v[56:57], 0
	v_mov_b64_e32 v[58:59], 0
	v_mov_b64_e32 v[60:61], 0
	v_mov_b64_e32 v[62:63], 0
	v_mov_b64_e32 v[64:65], 0
	v_mov_b64_e32 v[66:67], 0
	v_mov_b64_e32 v[68:69], 0
	v_mov_b64_e32 v[70:71], 0
	v_mov_b64_e32 v[72:73], 0
	v_mov_b64_e32 v[74:75], 0
	v_mov_b64_e32 v[76:77], 0
	v_mov_b64_e32 v[78:79], 0
	v_mov_b64_e32 v[80:81], 0
	v_mov_b64_e32 v[82:83], 0
	v_mov_b64_e32 v[84:85], 0
	v_mov_b64_e32 v[86:87], 0
	v_mov_b64_e32 v[88:89], 0
	v_mov_b64_e32 v[90:91], 0
	v_mov_b64_e32 v[92:93], 0
	v_mov_b64_e32 v[94:95], 0
	v_mov_b64_e32 v[98:99], 0
	v_mov_b64_e32 v[100:101], 0
	v_mov_b64_e32 v[102:103], 0
	v_mov_b64_e32 v[104:105], 0
	v_mov_b64_e32 v[106:107], 0
	v_mov_b64_e32 v[108:109], 0
	v_mov_b64_e32 v[110:111], 0
	v_mov_b64_e32 v[112:113], 0
	v_mov_b64_e32 v[114:115], 0
	v_mov_b64_e32 v[116:117], 0
	v_mov_b64_e32 v[118:119], 0
	v_mov_b64_e32 v[120:121], 0
	v_mov_b64_e32 v[122:123], 0
	v_mov_b64_e32 v[124:125], 0
	v_mov_b64_e32 v[126:127], 0
	v_mov_b64_e32 v[128:129], 0
